# P0 idx-k cache conversion done in one shot over all waves; P2 queue cache-conversion items rewritten as straight-line pipeline (3 groups of loads in flight, counted waits, nt loads)
# speedup vs baseline: 1.0481x; 1.0091x over previous
.LBB0_122:
	v_lshl_add_u64 v[2:3], v[38:39], 0, s[10:11]
	v_lshl_add_u64 v[2:3], v[2:3], 0, v[30:31]
	v_mov_b64_e32 v[4:5], 0x232a0800
	v_lshl_add_u64 v[46:47], v[2:3], 1, v[4:5]
	v_lshl_add_u64 v[2:3], v[34:35], 0, s[10:11]
	v_readlane_b32 s12, v251, 3
	v_lshl_add_u64 v[2:3], v[2:3], 0, v[30:31]
	v_readlane_b32 s13, v251, 4
	v_readlane_b32 s14, v251, 5
	v_readlane_b32 s15, v251, 6
	v_readlane_b32 s16, v251, 7
	v_readlane_b32 s17, v251, 8
	v_readlane_b32 s18, v251, 9
	v_readlane_b32 s19, v251, 10
	v_readlane_b32 s26, v251, 17
	v_readlane_b32 s27, v251, 18
	s_mov_b64 s[2:3], 0x232a0800
	v_lshl_add_u64 v[30:31], v[2:3], 1, v[4:5]
	s_mov_b32 s11, 0
	v_cndmask_b32_e64 v2, 0, 1, s[0:1]
	v_lshl_add_u64 v[32:33], s[26:27], 0, v[32:33]
	v_lshl_add_u64 v[42:43], v[42:43], 0, s[2:3]
	v_lshl_add_u64 v[44:45], v[44:45], 0, s[2:3]
	v_cmp_ne_u32_e64 s[0:1], 1, v2
	s_mov_b64 s[12:13], 0x40000
	s_mov_b64 s[14:15], 0x3ffff
	s_mov_b64 s[16:17], 0x100000
	s_mov_b64 s[18:19], 0x82000
	s_mov_b32 s10, s11
	v_readlane_b32 s38, v251, 19
	v_readlane_b32 s20, v251, 11
	v_readlane_b32 s21, v251, 12
	v_readlane_b32 s22, v251, 13
	v_readlane_b32 s23, v251, 14
	v_readlane_b32 s24, v251, 15
	v_readlane_b32 s25, v251, 16
	v_lshrrev_b32_e32 v84, 3, v28
	v_lshrrev_b32_e32 v85, 15, v84
	v_and_b32_e32 v86, 0x7fff, v84
	v_lshlrev_b32_e32 v87, 20, v85
	v_lshl_add_u32 v87, v86, 5, v87
	v_mul_u32_u24_e32 v88, 0x82000, v85
	v_lshl_add_u32 v88, v86, 4, v88
	v_readlane_b32 s20, v251, 17
	v_readlane_b32 s21, v251, 18
	s_add_u32 s2, s90, 0x232a0800
	s_addc_u32 s3, s91, 0
	s_add_u32 s4, s2, 0x208000
	s_addc_u32 s5, s3, 0
	s_add_u32 s22, s20, 0x400000
	s_addc_u32 s23, s21, 0
	s_nop 4
	global_load_dwordx4 v[68:71], v87, s[20:21] nt
	global_load_dwordx4 v[72:75], v87, s[20:21] offset:16 nt
	global_load_dwordx4 v[76:79], v87, s[22:23] nt
	global_load_dwordx4 v[80:83], v87, s[22:23] offset:16 nt
	s_waitcnt vmcnt(2)
	v_cvt_pk_bf16_f32 v68, v68, v69
	v_cvt_pk_bf16_f32 v69, v70, v71
	v_cvt_pk_bf16_f32 v70, v72, v73
	v_cvt_pk_bf16_f32 v71, v74, v75
	global_store_dwordx4 v88, v[68:71], s[2:3]
	s_waitcnt vmcnt(1)
	v_cvt_pk_bf16_f32 v76, v76, v77
	v_cvt_pk_bf16_f32 v77, v78, v79
	v_cvt_pk_bf16_f32 v78, v80, v81
	v_cvt_pk_bf16_f32 v79, v82, v83
	global_store_dwordx4 v88, v[76:79], s[4:5]

.LBB0_1116:
	v_writelane_b32 v251, s94, 50
	s_add_u32 s0, s90, 0x232a0800
	s_mul_i32 s7, s38, 0x82000
	v_writelane_b32 v251, s95, 51
	v_writelane_b32 v251, s0, 52
	s_addc_u32 s0, s91, 0
	v_writelane_b32 v251, s0, 54
	s_ashr_i32 s0, s38, 31
	v_writelane_b32 v251, s0, 56
	s_mul_hi_i32 s6, s38, 0x82000
	s_add_u32 s0, s90, s7
	s_addc_u32 s1, s91, s6
	s_add_u32 s4, s0, 0x23ab6800
	s_addc_u32 s5, s1, 0
	s_add_u32 s0, s90, 0x23ab67f8
	s_addc_u32 s1, s91, 0
	v_writelane_b32 v251, s0, 48
	s_waitcnt vmcnt(1)
	v_lshrrev_b32_e32 v1, 5, v192
	v_mov_b32_e32 v197, 0
	v_writelane_b32 v251, s1, 49
	s_add_u32 s0, s90, 0x22aa0800
	v_writelane_b32 v251, s0, 57
	s_addc_u32 s0, s91, 0
	v_lshlrev_b32_e32 v196, 4, v1
	v_writelane_b32 v251, s0, 59
	v_lshl_add_u64 v[2:3], s[90:91], 0, v[196:197]
	s_mov_b64 s[0:1], 0x20a80800
	s_add_u32 s62, s90, 0x236b0800
	v_and_b32_e32 v194, 31, v96
	v_lshl_add_u64 v[198:199], v[2:3], 0, s[0:1]
	s_addc_u32 s63, s91, 0
	s_lshl_b32 s0, s92, 5
	v_or_b32_e32 v2, s0, v194
	v_ashrrev_i32_e32 v3, 31, v2
	v_lshlrev_b32_e32 v200, 2, v1
	s_mov_b32 s65, s0
	v_lshlrev_b64 v[208:209], 7, v[2:3]
	s_movk_i32 s0, 0x4100
	v_mov_b64_e32 v[2:3], s[4:5]
	v_mad_u64_u32 v[2:3], s[0:1], v200, s0, v[2:3]
	s_cmp_lt_i32 s92, 32
	s_cselect_b64 s[0:1], -1, 0
	v_writelane_b32 v251, s0, 46
	s_mul_i32 s9, s92, 0x4100
	v_lshlrev_b32_e32 v196, 2, v194
	v_writelane_b32 v251, s1, 47
	s_mul_hi_i32 s8, s92, 0x4100
	s_add_u32 s0, s4, s9
	v_lshl_add_u64 v[210:211], v[2:3], 0, v[196:197]
	s_addc_u32 s1, s5, s8
	v_lshlrev_b32_e32 v196, 2, v192
	v_lshl_add_u64 v[212:213], s[0:1], 0, v[196:197]
	s_lshl_b32 s0, s92, 10
	s_add_u32 s94, s90, 0x33eb6800
	v_writelane_b32 v251, s4, 61
	s_addc_u32 s95, s91, 0
	s_add_i32 s93, s0, 0
	v_writelane_b32 v251, s5, 62
	s_add_u32 s0, s90, 0x20260800
	v_writelane_b32 v251, s0, 63
	s_addc_u32 s0, s91, 0
	v_lshlrev_b64 v[2:3], v192, -1
	v_writelane_b32 v250, s0, 0
	s_add_u32 s0, s90, 0x1fa40800
	v_writelane_b32 v250, s0, 1
	s_addc_u32 s0, s91, 0
	v_writelane_b32 v250, s0, 2
	s_add_u32 s0, s90, 0x17980800
	v_writelane_b32 v250, s0, 3
	s_addc_u32 s0, s91, 0
	v_writelane_b32 v250, s0, 4
	s_add_u32 s0, s90, 0x15900800
	v_writelane_b32 v250, s0, 5
	s_addc_u32 s0, s91, 0
	v_writelane_b32 v250, s0, 6
	s_add_u32 s0, s7, s9
	s_addc_u32 s1, s6, s8
	s_add_u32 s0, s90, s0
	s_addc_u32 s1, s91, s1
	s_add_u32 s0, s0, 0x23ab6800
	v_ashrrev_i32_e32 v97, 31, v96
	v_writelane_b32 v250, s0, 7
	s_addc_u32 s0, s1, 0
	v_lshlrev_b32_e32 v0, 3, v1
	v_not_b32_e32 v217, v3
	v_not_b32_e32 v216, v2
	v_writelane_b32 v250, s0, 9
	v_lshlrev_b64 v[2:3], 5, v[96:97]
	s_mov_b64 s[0:1], 0xc010
	s_mov_b32 s61, 0
	v_cmp_eq_u32_e64 s[2:3], 0, v96
	v_or_b32_e32 v229, 0x1000, v192
	v_mov_b32_e32 v195, v197
	v_or_b32_e32 v202, 24, v200
	v_mov_b32_e32 v203, v197
	v_or_b32_e32 v204, 16, v200
	v_mov_b32_e32 v205, v197
	v_or_b32_e32 v206, 8, v200
	v_mov_b32_e32 v207, v197
	v_mov_b32_e32 v201, v197
	v_mov_b32_e32 v193, v197
	v_lshl_add_u64 v[214:215], s[4:5], 0, v[196:197]
	v_cmp_eq_u32_e64 s[4:5], 0, v192
	v_lshlrev_b32_e32 v230, 6, v192
	v_lshl_add_u32 v231, v192, 3, s93
	v_lshlrev_b64 v[218:219], 3, v[96:97]
	v_xor_b32_e32 v232, 0x1e0, v192
	v_or_b32_e32 v221, 64, v192
	v_mov_b32_e32 v220, v192
	v_or_b32_e32 v233, 0x100, v194
	v_lshl_add_u64 v[222:223], v[2:3], 0, s[0:1]
	v_lshlrev_b32_e32 v210, 5, v96
	v_lshlrev_b32_e32 v211, 4, v96
	v_lshlrev_b32_e32 v224, 1, v0
	s_movk_i32 s0, 0x4000
	v_mov_b32_e32 v234, 0xff800000
	v_mov_b32_e32 v235, 0x4100
	v_lshrrev_b32_e32 v252, 5, v192
	v_and_b32_e32 v253, 31, v192
	v_mul_u32_u24_e32 v252, 0x240, v252
	v_lshl_add_u32 v252, v253, 2, v252
	s_mul_i32 s100, s92, 0x1200
	s_add_i32 s100, s100, 0x10000
	v_add_u32_e32 v252, s100, v252
	v_lshrrev_b32_e32 v253, 3, v192
	v_and_b32_e32 v254, 7, v192
	v_mul_u32_u24_e32 v255, 0x90, v253
	v_lshl_add_u32 v255, v254, 4, v255
	v_mul_u32_u24_e32 v253, 0x4100, v253
	v_lshl_add_u32 v254, v254, 4, v253
	v_add_u32_e32 v253, s100, v255
	v_readlane_b32 s98, v251, 61
	v_readlane_b32 s99, v251, 62
	s_branch .LBB0_1119

.LBB0_1471:
	s_lshl_b64 s[12:13], s[10:11], 2
	s_add_u32 s6, s6, s12
	s_addc_u32 s7, s7, s13
	s_lshl_b64 s[12:13], s[10:11], 1
	s_add_u32 s8, s8, s12
	s_addc_u32 s9, s9, s13
	global_load_dwordx4 v[44:47], v210, s[6:7] nt
	global_load_dwordx4 v[48:51], v210, s[6:7] offset:16 nt
	s_add_u32 s6, s6, s0
	s_addc_u32 s7, s7, 0
	global_load_dwordx4 v[52:55], v210, s[6:7] nt
	global_load_dwordx4 v[56:59], v210, s[6:7] offset:16 nt
	s_add_u32 s6, s6, s0
	s_addc_u32 s7, s7, 0
	global_load_dwordx4 v[60:63], v210, s[6:7] nt
	global_load_dwordx4 v[64:67], v210, s[6:7] offset:16 nt
	s_add_u32 s6, s6, s0
	s_addc_u32 s7, s7, 0
	global_load_dwordx4 v[68:71], v210, s[6:7] nt
	global_load_dwordx4 v[72:75], v210, s[6:7] offset:16 nt
	s_add_u32 s6, s6, s0
	s_addc_u32 s7, s7, 0
	global_load_dwordx4 v[76:79], v210, s[6:7] nt
	global_load_dwordx4 v[80:83], v210, s[6:7] offset:16 nt
	s_add_u32 s6, s6, s0
	s_addc_u32 s7, s7, 0
	global_load_dwordx4 v[84:87], v210, s[6:7] nt
	global_load_dwordx4 v[88:91], v210, s[6:7] offset:16 nt
	s_add_u32 s6, s6, s0
	s_addc_u32 s7, s7, 0
	global_load_dwordx4 v[92:95], v210, s[6:7] nt
	global_load_dwordx4 v[96:99], v210, s[6:7] offset:16 nt
	s_add_u32 s6, s6, s0
	s_addc_u32 s7, s7, 0
	global_load_dwordx4 v[100:103], v210, s[6:7] nt
	global_load_dwordx4 v[104:107], v210, s[6:7] offset:16 nt
	s_add_u32 s6, s6, s0
	s_addc_u32 s7, s7, 0
	global_load_dwordx4 v[108:111], v210, s[6:7] nt
	global_load_dwordx4 v[112:115], v210, s[6:7] offset:16 nt
	s_add_u32 s6, s6, s0
	s_addc_u32 s7, s7, 0
	global_load_dwordx4 v[116:119], v210, s[6:7] nt
	global_load_dwordx4 v[120:123], v210, s[6:7] offset:16 nt
	s_add_u32 s6, s6, s0
	s_addc_u32 s7, s7, 0
	global_load_dwordx4 v[124:127], v210, s[6:7] nt
	global_load_dwordx4 v[128:131], v210, s[6:7] offset:16 nt
	s_add_u32 s6, s6, s0
	s_addc_u32 s7, s7, 0
	global_load_dwordx4 v[132:135], v210, s[6:7] nt
	global_load_dwordx4 v[136:139], v210, s[6:7] offset:16 nt
	s_add_u32 s6, s6, s0
	s_addc_u32 s7, s7, 0
	s_waitcnt vmcnt(16)
	v_cvt_pk_bf16_f32 v44, v44, v45
	v_cvt_pk_bf16_f32 v45, v46, v47
	v_cvt_pk_bf16_f32 v46, v48, v49
	v_cvt_pk_bf16_f32 v47, v50, v51
	global_store_dwordx4 v211, v[44:47], s[8:9]
	s_add_u32 s8, s8, 0x2000
	s_addc_u32 s9, s9, 0
	v_cvt_pk_bf16_f32 v52, v52, v53
	v_cvt_pk_bf16_f32 v53, v54, v55
	v_cvt_pk_bf16_f32 v54, v56, v57
	v_cvt_pk_bf16_f32 v55, v58, v59
	global_store_dwordx4 v211, v[52:55], s[8:9]
	s_add_u32 s8, s8, 0x2000
	s_addc_u32 s9, s9, 0
	v_cvt_pk_bf16_f32 v60, v60, v61
	v_cvt_pk_bf16_f32 v61, v62, v63
	v_cvt_pk_bf16_f32 v62, v64, v65
	v_cvt_pk_bf16_f32 v63, v66, v67
	global_store_dwordx4 v211, v[60:63], s[8:9]
	s_add_u32 s8, s8, 0x2000
	s_addc_u32 s9, s9, 0
	v_cvt_pk_bf16_f32 v68, v68, v69
	v_cvt_pk_bf16_f32 v69, v70, v71
	v_cvt_pk_bf16_f32 v70, v72, v73
	v_cvt_pk_bf16_f32 v71, v74, v75
	global_store_dwordx4 v211, v[68:71], s[8:9]
	s_add_u32 s8, s8, 0x2000
	s_addc_u32 s9, s9, 0
	global_load_dwordx4 v[44:47], v210, s[6:7] nt
	global_load_dwordx4 v[48:51], v210, s[6:7] offset:16 nt
	s_add_u32 s6, s6, s0
	s_addc_u32 s7, s7, 0
	global_load_dwordx4 v[52:55], v210, s[6:7] nt
	global_load_dwordx4 v[56:59], v210, s[6:7] offset:16 nt
	s_add_u32 s6, s6, s0
	s_addc_u32 s7, s7, 0
	global_load_dwordx4 v[60:63], v210, s[6:7] nt
	global_load_dwordx4 v[64:67], v210, s[6:7] offset:16 nt
	s_add_u32 s6, s6, s0
	s_addc_u32 s7, s7, 0
	global_load_dwordx4 v[68:71], v210, s[6:7] nt
	global_load_dwordx4 v[72:75], v210, s[6:7] offset:16 nt
	s_add_u32 s6, s6, s0
	s_addc_u32 s7, s7, 0
	s_waitcnt vmcnt(20)
	v_cvt_pk_bf16_f32 v76, v76, v77
	v_cvt_pk_bf16_f32 v77, v78, v79
	v_cvt_pk_bf16_f32 v78, v80, v81
	v_cvt_pk_bf16_f32 v79, v82, v83
	global_store_dwordx4 v211, v[76:79], s[8:9]
	s_add_u32 s8, s8, 0x2000
	s_addc_u32 s9, s9, 0
	v_cvt_pk_bf16_f32 v84, v84, v85
	v_cvt_pk_bf16_f32 v85, v86, v87
	v_cvt_pk_bf16_f32 v86, v88, v89
	v_cvt_pk_bf16_f32 v87, v90, v91
	global_store_dwordx4 v211, v[84:87], s[8:9]
	s_add_u32 s8, s8, 0x2000
	s_addc_u32 s9, s9, 0
	v_cvt_pk_bf16_f32 v92, v92, v93
	v_cvt_pk_bf16_f32 v93, v94, v95
	v_cvt_pk_bf16_f32 v94, v96, v97
	v_cvt_pk_bf16_f32 v95, v98, v99
	global_store_dwordx4 v211, v[92:95], s[8:9]
	s_add_u32 s8, s8, 0x2000
	s_addc_u32 s9, s9, 0
	v_cvt_pk_bf16_f32 v100, v100, v101
	v_cvt_pk_bf16_f32 v101, v102, v103
	v_cvt_pk_bf16_f32 v102, v104, v105
	v_cvt_pk_bf16_f32 v103, v106, v107
	global_store_dwordx4 v211, v[100:103], s[8:9]
	s_add_u32 s8, s8, 0x2000
	s_addc_u32 s9, s9, 0
	s_waitcnt vmcnt(16)
	v_cvt_pk_bf16_f32 v108, v108, v109
	v_cvt_pk_bf16_f32 v109, v110, v111
	v_cvt_pk_bf16_f32 v110, v112, v113
	v_cvt_pk_bf16_f32 v111, v114, v115
	global_store_dwordx4 v211, v[108:111], s[8:9]
	s_add_u32 s8, s8, 0x2000
	s_addc_u32 s9, s9, 0
	v_cvt_pk_bf16_f32 v116, v116, v117
	v_cvt_pk_bf16_f32 v117, v118, v119
	v_cvt_pk_bf16_f32 v118, v120, v121
	v_cvt_pk_bf16_f32 v119, v122, v123
	global_store_dwordx4 v211, v[116:119], s[8:9]
	s_add_u32 s8, s8, 0x2000
	s_addc_u32 s9, s9, 0
	v_cvt_pk_bf16_f32 v124, v124, v125
	v_cvt_pk_bf16_f32 v125, v126, v127
	v_cvt_pk_bf16_f32 v126, v128, v129
	v_cvt_pk_bf16_f32 v127, v130, v131
	global_store_dwordx4 v211, v[124:127], s[8:9]
	s_add_u32 s8, s8, 0x2000
	s_addc_u32 s9, s9, 0
	v_cvt_pk_bf16_f32 v132, v132, v133
	v_cvt_pk_bf16_f32 v133, v134, v135
	v_cvt_pk_bf16_f32 v134, v136, v137
	v_cvt_pk_bf16_f32 v135, v138, v139
	global_store_dwordx4 v211, v[132:135], s[8:9]
	s_add_u32 s8, s8, 0x2000
	s_addc_u32 s9, s9, 0
	s_waitcnt vmcnt(8)
	v_cvt_pk_bf16_f32 v44, v44, v45
	v_cvt_pk_bf16_f32 v45, v46, v47
	v_cvt_pk_bf16_f32 v46, v48, v49
	v_cvt_pk_bf16_f32 v47, v50, v51
	global_store_dwordx4 v211, v[44:47], s[8:9]
	s_add_u32 s8, s8, 0x2000
	s_addc_u32 s9, s9, 0
	v_cvt_pk_bf16_f32 v52, v52, v53
	v_cvt_pk_bf16_f32 v53, v54, v55
	v_cvt_pk_bf16_f32 v54, v56, v57
	v_cvt_pk_bf16_f32 v55, v58, v59
	global_store_dwordx4 v211, v[52:55], s[8:9]
	s_add_u32 s8, s8, 0x2000
	s_addc_u32 s9, s9, 0
	v_cvt_pk_bf16_f32 v60, v60, v61
	v_cvt_pk_bf16_f32 v61, v62, v63
	v_cvt_pk_bf16_f32 v62, v64, v65
	v_cvt_pk_bf16_f32 v63, v66, v67
	global_store_dwordx4 v211, v[60:63], s[8:9]
	s_add_u32 s8, s8, 0x2000
	s_addc_u32 s9, s9, 0
	v_cvt_pk_bf16_f32 v68, v68, v69
	v_cvt_pk_bf16_f32 v69, v70, v71
	v_cvt_pk_bf16_f32 v70, v72, v73
	v_cvt_pk_bf16_f32 v71, v74, v75
	global_store_dwordx4 v211, v[68:71], s[8:9]
	s_add_u32 s8, s8, 0x2000
	s_addc_u32 s9, s9, 0
	s_branch .LBB0_1117
